# P1 u0 phase: fully unrolled loads (28 in flight) fast path for grid 512
# baseline (speedup 1.0000x reference)
.LBB0_118:
	s_or_b64 exec, exec, s[2:3]
	s_load_dwordx16 s[36:51], s[0:1], 0x158
	s_load_dwordx16 s[4:19], s[0:1], 0x1d0
	s_waitcnt lgkmcnt(0)
	v_mov_b32_e32 v0, v250
	s_barrier
	v_writelane_b32 v253, s4, 6
	s_nop 0
	v_lshl_add_u32 v8, s55, 8, v0
	v_writelane_b32 v253, s5, 7
	v_writelane_b32 v253, s6, 8
	v_writelane_b32 v253, s7, 9
	v_writelane_b32 v253, s8, 10
	v_writelane_b32 v253, s9, 11
	v_writelane_b32 v253, s10, 12
	v_writelane_b32 v253, s11, 13
	v_writelane_b32 v253, s12, 14
	v_writelane_b32 v253, s13, 15
	v_writelane_b32 v253, s14, 16
	v_writelane_b32 v253, s15, 17
	v_writelane_b32 v253, s16, 18
	v_writelane_b32 v253, s17, 19
	v_writelane_b32 v253, s18, 20
	v_writelane_b32 v253, s19, 21
	s_load_dwordx4 s[4:7], s[0:1], 0x210
	s_mov_b32 s0, 0x100000
	v_cmp_gt_i32_e32 vcc, s0, v8
	s_waitcnt lgkmcnt(0)
	v_writelane_b32 v253, s4, 22
	s_nop 1
	v_writelane_b32 v253, s5, 23
	v_writelane_b32 v253, s6, 24
	v_writelane_b32 v253, s7, 25
	s_and_saveexec_b64 s[2:3], vcc
	s_cbranch_execz .LBB0_125
	s_cmp_lg_u32 s92, 0x200
	s_cbranch_scc1 .Lp1_orig
	v_readlane_b32 s12, v254, 2
	v_readlane_b32 s13, v254, 3
	v_readlane_b32 s14, v254, 4
	v_readlane_b32 s15, v254, 5
	v_and_b32_e32 v1, 0x7f, v8
	v_lshrrev_b32_e32 v2, 7, v8
	v_lshlrev_b32_e32 v3, 5, v1
	v_lshl_add_u32 v4, v2, 12, v3
	v_lshlrev_b32_e32 v5, 4, v1
	v_lshl_add_u32 v5, v2, 11, v5
	v_add_u32_e32 v6, 0x1000, v3
	s_mov_b64 s[98:99], s[12:13]
	global_load_dwordx4 v[16:19], v4, s[98:99]
	global_load_dwordx4 v[20:23], v4, s[98:99] offset:16
	s_add_u32 s98, s98, 0x400000
	s_addc_u32 s99, s99, 0
	global_load_dwordx4 v[24:27], v4, s[98:99]
	global_load_dwordx4 v[28:31], v4, s[98:99] offset:16
	s_add_u32 s98, s98, 0x400000
	s_addc_u32 s99, s99, 0
	global_load_dwordx4 v[32:35], v4, s[98:99]
	global_load_dwordx4 v[36:39], v4, s[98:99] offset:16
	s_add_u32 s98, s98, 0x400000
	s_addc_u32 s99, s99, 0
	global_load_dwordx4 v[40:43], v4, s[98:99]
	global_load_dwordx4 v[44:47], v4, s[98:99] offset:16
	s_mov_b64 s[98:99], s[14:15]
	global_load_dwordx4 v[48:51], v4, s[98:99]
	global_load_dwordx4 v[52:55], v4, s[98:99] offset:16
	s_add_u32 s98, s98, 0x400000
	s_addc_u32 s99, s99, 0
	global_load_dwordx4 v[56:59], v4, s[98:99]
	global_load_dwordx4 v[60:63], v4, s[98:99] offset:16
	s_add_u32 s98, s98, 0x400000
	s_addc_u32 s99, s99, 0
	global_load_dwordx4 v[64:67], v4, s[98:99]
	global_load_dwordx4 v[68:71], v4, s[98:99] offset:16
	s_add_u32 s98, s98, 0x400000
	s_addc_u32 s99, s99, 0
	global_load_dwordx4 v[72:75], v4, s[98:99]
	global_load_dwordx4 v[76:79], v4, s[98:99] offset:16
	s_mov_b64 s[98:99], s[56:57]
	global_load_dwordx4 v[80:83], v3, s[98:99]
	global_load_dwordx4 v[84:87], v3, s[98:99] offset:16
	global_load_dwordx4 v[88:91], v6, s[98:99]
	global_load_dwordx4 v[92:95], v6, s[98:99] offset:16
	s_add_u32 s98, s98, 0x6000
	s_addc_u32 s99, s99, 0
	global_load_dwordx4 v[96:99], v3, s[98:99]
	global_load_dwordx4 v[100:103], v3, s[98:99] offset:16
	global_load_dwordx4 v[104:107], v6, s[98:99]
	global_load_dwordx4 v[108:111], v6, s[98:99] offset:16
	s_add_u32 s98, s98, 0x6000
	s_addc_u32 s99, s99, 0
	global_load_dwordx4 v[112:115], v3, s[98:99]
	global_load_dwordx4 v[116:119], v3, s[98:99] offset:16
	global_load_dwordx4 v[120:123], v6, s[98:99]
	global_load_dwordx4 v[124:127], v6, s[98:99] offset:16
	s_mov_b64 s[98:99], s[36:37]
	s_waitcnt vmcnt(0)
	v_pk_add_f32 v[88:89], v[88:89], 1.0 op_sel_hi:[1,0]
	v_pk_add_f32 v[90:91], v[90:91], 1.0 op_sel_hi:[1,0]
	v_pk_add_f32 v[92:93], v[92:93], 1.0 op_sel_hi:[1,0]
	v_pk_add_f32 v[94:95], v[94:95], 1.0 op_sel_hi:[1,0]
	v_pk_add_f32 v[104:105], v[104:105], 1.0 op_sel_hi:[1,0]
	v_pk_add_f32 v[106:107], v[106:107], 1.0 op_sel_hi:[1,0]
	v_pk_add_f32 v[108:109], v[108:109], 1.0 op_sel_hi:[1,0]
	v_pk_add_f32 v[110:111], v[110:111], 1.0 op_sel_hi:[1,0]
	v_pk_add_f32 v[120:121], v[120:121], 1.0 op_sel_hi:[1,0]
	v_pk_add_f32 v[122:123], v[122:123], 1.0 op_sel_hi:[1,0]
	v_pk_add_f32 v[124:125], v[124:125], 1.0 op_sel_hi:[1,0]
	v_pk_add_f32 v[126:127], v[126:127], 1.0 op_sel_hi:[1,0]
	v_pk_fma_f32 v[16:17], v[16:17], v[88:89], v[80:81]
	v_pk_fma_f32 v[18:19], v[18:19], v[90:91], v[82:83]
	v_pk_fma_f32 v[20:21], v[20:21], v[92:93], v[84:85]
	v_pk_fma_f32 v[22:23], v[22:23], v[94:95], v[86:87]
	v_cvt_pk_bf16_f32 v128, v16, v17
	v_cvt_pk_bf16_f32 v129, v18, v19
	v_cvt_pk_bf16_f32 v130, v20, v21
	v_cvt_pk_bf16_f32 v131, v22, v23
	global_store_dwordx4 v5, v[128:131], s[98:99]
	v_pk_fma_f32 v[24:25], v[24:25], v[88:89], v[80:81]
	v_pk_fma_f32 v[26:27], v[26:27], v[90:91], v[82:83]
	v_pk_fma_f32 v[28:29], v[28:29], v[92:93], v[84:85]
	v_pk_fma_f32 v[30:31], v[30:31], v[94:95], v[86:87]
	v_cvt_pk_bf16_f32 v132, v24, v25
	v_cvt_pk_bf16_f32 v133, v26, v27
	v_cvt_pk_bf16_f32 v134, v28, v29
	v_cvt_pk_bf16_f32 v135, v30, v31
	s_add_u32 s98, s98, 0x200000
	s_addc_u32 s99, s99, 0
	global_store_dwordx4 v5, v[132:135], s[98:99]
	v_pk_fma_f32 v[32:33], v[32:33], v[88:89], v[80:81]
	v_pk_fma_f32 v[34:35], v[34:35], v[90:91], v[82:83]
	v_pk_fma_f32 v[36:37], v[36:37], v[92:93], v[84:85]
	v_pk_fma_f32 v[38:39], v[38:39], v[94:95], v[86:87]
	v_cvt_pk_bf16_f32 v136, v32, v33
	v_cvt_pk_bf16_f32 v137, v34, v35
	v_cvt_pk_bf16_f32 v138, v36, v37
	v_cvt_pk_bf16_f32 v139, v38, v39
	s_add_u32 s98, s98, 0x200000
	s_addc_u32 s99, s99, 0
	global_store_dwordx4 v5, v[136:139], s[98:99]
	v_pk_fma_f32 v[40:41], v[40:41], v[88:89], v[80:81]
	v_pk_fma_f32 v[42:43], v[42:43], v[90:91], v[82:83]
	v_pk_fma_f32 v[44:45], v[44:45], v[92:93], v[84:85]
	v_pk_fma_f32 v[46:47], v[46:47], v[94:95], v[86:87]
	v_cvt_pk_bf16_f32 v140, v40, v41
	v_cvt_pk_bf16_f32 v141, v42, v43
	v_cvt_pk_bf16_f32 v142, v44, v45
	v_cvt_pk_bf16_f32 v143, v46, v47
	s_add_u32 s98, s98, 0x200000
	s_addc_u32 s99, s99, 0
	global_store_dwordx4 v5, v[140:143], s[98:99]
	v_pk_fma_f32 v[48:49], v[48:49], v[104:105], v[96:97]
	v_pk_fma_f32 v[50:51], v[50:51], v[106:107], v[98:99]
	v_pk_fma_f32 v[52:53], v[52:53], v[108:109], v[100:101]
	v_pk_fma_f32 v[54:55], v[54:55], v[110:111], v[102:103]
	v_cvt_pk_bf16_f32 v144, v48, v49
	v_cvt_pk_bf16_f32 v145, v50, v51
	v_cvt_pk_bf16_f32 v146, v52, v53
	v_cvt_pk_bf16_f32 v147, v54, v55
	s_add_u32 s98, s98, 0x200000
	s_addc_u32 s99, s99, 0
	global_store_dwordx4 v5, v[144:147], s[98:99]
	v_pk_fma_f32 v[56:57], v[56:57], v[104:105], v[96:97]
	v_pk_fma_f32 v[58:59], v[58:59], v[106:107], v[98:99]
	v_pk_fma_f32 v[60:61], v[60:61], v[108:109], v[100:101]
	v_pk_fma_f32 v[62:63], v[62:63], v[110:111], v[102:103]
	v_cvt_pk_bf16_f32 v148, v56, v57
	v_cvt_pk_bf16_f32 v149, v58, v59
	v_cvt_pk_bf16_f32 v150, v60, v61
	v_cvt_pk_bf16_f32 v151, v62, v63
	s_add_u32 s98, s98, 0x200000
	s_addc_u32 s99, s99, 0
	global_store_dwordx4 v5, v[148:151], s[98:99]
	v_pk_fma_f32 v[64:65], v[64:65], v[120:121], v[112:113]
	v_pk_fma_f32 v[66:67], v[66:67], v[122:123], v[114:115]
	v_pk_fma_f32 v[68:69], v[68:69], v[124:125], v[116:117]
	v_pk_fma_f32 v[70:71], v[70:71], v[126:127], v[118:119]
	v_cvt_pk_bf16_f32 v152, v64, v65
	v_cvt_pk_bf16_f32 v153, v66, v67
	v_cvt_pk_bf16_f32 v154, v68, v69
	v_cvt_pk_bf16_f32 v155, v70, v71
	s_add_u32 s98, s98, 0x200000
	s_addc_u32 s99, s99, 0
	global_store_dwordx4 v5, v[152:155], s[98:99]
	v_pk_fma_f32 v[72:73], v[72:73], v[120:121], v[112:113]
	v_pk_fma_f32 v[74:75], v[74:75], v[122:123], v[114:115]
	v_pk_fma_f32 v[76:77], v[76:77], v[124:125], v[116:117]
	v_pk_fma_f32 v[78:79], v[78:79], v[126:127], v[118:119]
	v_cvt_pk_bf16_f32 v156, v72, v73
	v_cvt_pk_bf16_f32 v157, v74, v75
	v_cvt_pk_bf16_f32 v158, v76, v77
	v_cvt_pk_bf16_f32 v159, v78, v79
	s_add_u32 s98, s98, 0x200000
	s_addc_u32 s99, s99, 0
	global_store_dwordx4 v5, v[156:159], s[98:99]
	s_branch .LBB0_125
.Lp1_orig:
	v_lshlrev_b32_e32 v0, 3, v0
	s_lshl_b32 s6, s92, 8
	v_lshl_add_u32 v9, s55, 11, v0
	s_lshl_b32 s7, s92, 11
	s_mov_b64 s[4:5], 0
	s_movk_i32 s8, 0x1000
	v_mov_b32_e32 v1, 0
	v_mov_b64_e32 v[2:3], s[56:57]
	s_branch .LBB0_121
